# band attention: next item's inputs requested two per half-step over the item's last 8 half-steps; dummy requests no longer target an address register (run 1)
# baseline (speedup 1.0000x reference)
.Lbs_noskew:
	global_load_dwordx4 v[16:19], v[230:231], off
	global_load_dwordx4 v[20:23], v[232:233], off
	v_add_co_u32_e32 v230, vcc, 0x50000, v230
	s_nop 1
	v_addc_co_u32_e32 v231, vcc, 0, v231, vcc
	v_add_co_u32_e32 v232, vcc, 0x50000, v232
	s_nop 1
	v_addc_co_u32_e32 v233, vcc, 0, v233, vcc
	global_load_dwordx4 v[8:11], v[8:9], off
	global_load_dwordx4 v[12:15], v[12:13], off offset:64
	global_load_dwordx4 v[24:27], v[230:231], off
	global_load_dwordx4 v[28:31], v[232:233], off
	s_waitcnt vmcnt(0)
	s_cmp_ge_u32 s11, 8
	s_cbranch_scc0 .Lbs_nopre
	s_branch .Lcip_pre

.Lbs_nopre:
.LBB0_1043:
	s_and_saveexec_b64 s[4:5], s[36:37]
	v_mul_f32_e32 v237, 0x3fb8aa3b, v237
	ds_write_b32 v121, v237 offset:36864
	s_or_b64 exec, exec, s[4:5]
	s_add_i32 s3, s11, s13
	s_add_i32 s4, s3, -8
	s_cmp_gt_i32 s3, 7
	s_cselect_b32 s27, s4, 0
	v_add_u32_e32 v32, s1, v144
	s_sub_i32 s28, s21, s11
	s_mul_hi_i32 s1, s0, 0x1400000
	s_mul_i32 s0, s0, 0x1400000
	s_add_u32 s0, s24, s0
	s_addc_u32 s1, s25, s1
	v_subrev_u32_e32 v133, s8, v32
	s_cmp_ge_u32 s11, 8
	s_cselect_b32 s4, s13, 0
	s_sub_i32 s27, s27, s4
	s_sub_i32 s3, s3, s4
	s_add_i32 s28, s28, s4
	s_lshl_b32 s5, s4, 6
	v_subrev_u32_e32 v133, s5, v133
	s_add_i32 s5, s30, 9
	s_cmp_ge_u32 s11, 8
	s_cselect_b32 s2, s5, s2
	v_add_u32_e32 v34, s8, v114
	v_mov_b64_e32 v[32:33], s[0:1]
	s_movk_i32 s0, 0x1400
	v_mad_i64_i32 v[32:33], s[0:1], v34, s0, v[32:33]
	v_mov_b32_e32 v34, v153
	v_mov_b32_e32 v35, v153
	v_lshl_add_u64 v[140:141], v[128:129], 0, v[32:33]
	s_cmp_ge_u32 s11, 8
	s_cselect_b32 s4, 0xf0000, 0
	s_mov_b32 s5, 0
	v_lshl_add_u64 v[140:141], v[140:141], 0, s[4:5]
	s_add_i32 s9, s26, s90
	s_cmpk_gt_i32 s9, 0x5ff
	s_cbranch_scc1 .Lnx_done
	s_mul_hi_i32 s5, s9, 0x2aaaaaab
	s_ashr_i32 s6, s5, 1
	s_mul_i32 s7, s6, 12
	s_sub_i32 s7, s9, s7
	s_and_b32 s8, s6, 15
	s_ashr_i32 s5, s5, 5
	s_lshl_b32 s4, s5, 12
	s_lshl_b32 s6, s8, 8
	s_or_b32 s6, s4, s6
	s_add_i32 s6, s6, s14
	s_mul_i32 s6, s6, 0x1400
	s_lshl_b32 s9, s7, 7
	s_add_i32 s6, s6, s9
	v_add3_u32 v188, v152, v130, s6
	s_lshl_b32 s6, s8, 2
	s_add_i32 s6, s6, -8
	s_cmp_gt_u32 s8, 1
	s_cselect_b32 s6, s6, 0
	s_lshl_b32 s6, s6, 6
	s_add_i32 s6, s6, s4
	v_add_u32_e32 v189, s6, v114
	v_mul_lo_u32 v189, v189, s40
	v_or_b32_e32 v189, v189, v112
	v_lshl_add_u32 v189, v189, 1, s9
	s_sub_i32 s8, s2, s30
	s_mov_b32 s4, 7
.Lnx_loop:
	s_cmp_lt_i32 s4, s8
	s_cbranch_scc1 .Lnx_done
	s_mov_b32 s5, s4
	s_mov_b32 s9, 2
	s_branch .Lside
.Lside_ret_p:
	s_add_i32 s4, s4, -1
	s_branch .Lnx_loop
.Lnx_done:
	v_mov_b32_e32 v32, v153
	v_mov_b32_e32 v33, v153
	v_mov_b64_e32 v[38:39], v[34:35]
	v_mov_b64_e32 v[50:51], v[34:35]
	v_mov_b64_e32 v[42:43], v[34:35]
	v_mov_b64_e32 v[46:47], v[34:35]
	v_mov_b64_e32 v[54:55], v[34:35]
	v_mov_b64_e32 v[62:63], v[34:35]
	v_mov_b64_e32 v[58:59], v[34:35]
	v_mov_b32_e32 v131, 0
	v_mov_b32_e32 v137, 0xf149f2ca
	v_mov_b64_e32 v[36:37], v[32:33]
	v_mov_b64_e32 v[48:49], v[32:33]
	v_mov_b64_e32 v[40:41], v[32:33]
	v_mov_b64_e32 v[44:45], v[32:33]
	v_mov_b64_e32 v[52:53], v[32:33]
	v_mov_b64_e32 v[60:61], v[32:33]
	v_mov_b64_e32 v[56:57], v[32:33]
	v_mov_b32_e32 v139, 0xf149f2ca
	v_mov_b32_e32 v135, 0
.LBB0_1044:
	s_add_i32 s29, s30, 2
	s_cmp_ge_i32 s29, s2
	s_cselect_b64 s[0:1], -1, 0
	s_and_b64 vcc, exec, s[0:1]
	s_cmp_ge_u32 s11, 8
	s_cselect_b32 s4, 3, 0
	s_add_i32 s4, s4, s30
	s_mul_hi_u32 s6, s4, 0x33333334
	s_mul_i32 s6, s6, 5
	s_sub_i32 s4, s4, s6
	s_mul_i32 s6, s4, 0x6c00
	s_add_i32 s6, s6, 0xffffc800
	s_mul_i32 s5, s4, 0x2400
	s_cmp_gt_u32 s4, 1
	s_cselect_b32 s5, s6, s5
	v_add_u32_e32 v234, s5, v123
	s_waitcnt vmcnt(7)
	ds_write_b128 v234, v[16:19]
	s_waitcnt vmcnt(6)
	ds_write_b128 v234, v[20:23] offset:18432
	s_waitcnt lgkmcnt(0)
	s_barrier
	v_add_co_u32_e32 v20, vcc, 0xfffb0000, v140
	s_nop 1
	v_addc_co_u32_e32 v21, vcc, -1, v141, vcc
	global_load_dwordx4 v[16:19], v[20:21], off offset:-1536
	s_nop 0
	global_load_dwordx4 v[20:23], v[20:21], off
	s_sub_i32 s5, s2, s30
	s_add_i32 s5, s5, -1
	s_mov_b32 s9, 0
	s_branch .Lside

.LBB0_1057:
	s_add_i32 s5, s30, 3
	s_cmp_ge_i32 s5, s2
	s_cmp_ge_u32 s11, 8
	s_cselect_b32 s5, 4, 1
	s_add_i32 s5, s5, s30
	s_mul_hi_u32 s7, s5, 0x33333334
	s_mul_i32 s7, s7, 5
	s_sub_i32 s5, s5, s7
	s_mul_i32 s7, s5, 0x6c00
	s_add_i32 s7, s7, 0xffffc800
	s_mul_i32 s6, s5, 0x2400
	s_cmp_gt_u32 s5, 1
	s_cselect_b32 s6, s7, s6
	s_add_i32 s6, s6, 0xffffdc00
	v_add_u32_e32 v234, s6, v123
	s_waitcnt vmcnt(7)
	ds_write_b128 v234, v[24:27] offset:9216
	s_waitcnt vmcnt(6)
	ds_write_b128 v234, v[28:31] offset:27648
	s_waitcnt lgkmcnt(0)
	s_barrier
	global_load_dwordx4 v[24:27], v[140:141], off offset:-1536
	global_load_dwordx4 v[28:31], v[140:141], off
	s_sub_i32 s5, s2, s30
	s_add_i32 s5, s5, -2
	s_mov_b32 s9, 1
	s_branch .Lside

.Lside:
	s_add_i32 s6, s26, s90
	s_cmpk_gt_i32 s6, 0x5ff
	s_cbranch_scc1 .Lside_dummy
	s_cmp_eq_u32 s5, 7
	s_cbranch_scc1 .Lside_7
	s_cmp_eq_u32 s5, 6
	s_cbranch_scc1 .Lside_6
	s_cmp_eq_u32 s5, 5
	s_cbranch_scc1 .Lside_5
	s_cmp_eq_u32 s5, 4
	s_cbranch_scc1 .Lside_4
	s_cmp_eq_u32 s5, 3
	s_cbranch_scc1 .Lside_3
	s_cmp_eq_u32 s5, 2
	s_cbranch_scc1 .Lside_2
	s_cmp_eq_u32 s5, 1
	s_cbranch_scc1 .Lside_1
	s_cmp_eq_u32 s5, 0
	s_cbranch_scc1 .Lside_0
.Lside_dummy:
	global_load_dword v195, v153, s[60:61]
	global_load_dword v195, v153, s[60:61] offset:64
	s_branch .Lside_ret
.Lside_7:
	global_load_dwordx4 v[176:179], v188, s[60:61]
	global_load_dwordx4 v[180:183], v188, s[60:61] offset:64
	s_branch .Lside_ret
.Lside_6:
	v_add_u32_e32 v246, 0x14000, v188
	global_load_dwordx4 v[184:187], v246, s[60:61]
	global_load_dwordx4 v[196:199], v246, s[60:61] offset:64
	s_branch .Lside_ret
.Lside_5:
	s_mul_hi_i32 s7, s6, 0x2aaaaaab
	s_ashr_i32 s7, s7, 1
	s_and_b32 s7, s7, 15
	s_cmp_gt_u32 s7, 1
	s_cbranch_scc0 .Lside_dummy
	s_mov_b32 s100, s94
	s_mov_b32 s101, s19
	s_mov_b32 s6, s31
	s_mov_b32 s7, s33
	v_add_u32_e32 v246, 0x0, v189
	global_load_dwordx4 v[206:209], v246, s[100:101]
	global_load_dwordx4 v[210:213], v246, s[6:7]
	s_branch .Lside_ret
.Lside_4:
	s_mul_hi_i32 s7, s6, 0x2aaaaaab
	s_ashr_i32 s7, s7, 1
	s_and_b32 s7, s7, 15
	s_cmp_gt_u32 s7, 1
	s_cbranch_scc0 .Lside_dummy
	s_mov_b32 s100, s94
	s_mov_b32 s101, s19
	s_mov_b32 s6, s31
	s_mov_b32 s7, s33
	v_add_u32_e32 v246, 0x50000, v189
	global_load_dwordx4 v[214:217], v246, s[100:101]
	global_load_dwordx4 v[218:221], v246, s[6:7]
	s_branch .Lside_ret
.Lside_3:
	s_mul_hi_i32 s7, s6, 0x2aaaaaab
	s_ashr_i32 s7, s7, 1
	s_and_b32 s7, s7, 15
	s_cmp_gt_u32 s7, 1
	s_cbranch_scc0 .Lside_dummy
	s_mov_b32 s100, s94
	s_mov_b32 s101, s19
	s_mov_b32 s6, s31
	s_mov_b32 s7, s33
	v_add_u32_e32 v246, 0xa0000, v189
	global_load_dwordx4 v[222:225], v246, s[100:101]
	global_load_dwordx4 v[226:229], v246, s[6:7]
	s_branch .Lside_ret
.Lside_2:
	s_mul_hi_i32 s7, s6, 0x2aaaaaab
	s_ashr_i32 s7, s7, 1
	s_and_b32 s7, s7, 15
	s_cmp_gt_u32 s7, 1
	s_cselect_b32 s7, 0xf0000, 0
	v_add_u32_e32 v246, s7, v189
	s_mov_b32 s100, s94
	s_mov_b32 s101, s19
	s_mov_b32 s6, s31
	s_mov_b32 s7, s33
	global_load_dwordx4 v[238:241], v246, s[100:101]
	global_load_dwordx4 v[242:245], v246, s[6:7]
	s_branch .Lside_ret
.Lside_1:
	s_mul_hi_i32 s7, s6, 0x2aaaaaab
	s_ashr_i32 s7, s7, 1
	s_and_b32 s7, s7, 15
	s_cmp_gt_u32 s7, 1
	s_cselect_b32 s7, 0xf0000, 0
	s_add_i32 s7, s7, 0x50000
	v_add_u32_e32 v246, s7, v189
	s_mov_b32 s100, s94
	s_mov_b32 s101, s19
	s_mov_b32 s6, s31
	s_mov_b32 s7, s33
	global_load_dwordx4 v[230:233], v246, s[100:101]
	global_load_dwordx4 v[200:203], v246, s[6:7]
	s_branch .Lside_ret
.Lside_0:
	global_load_dword v195, v153, s[60:61]
	s_mul_hi_i32 s7, s6, 0x2aaaaaab
	s_ashr_i32 s7, s7, 1
	s_mul_i32 s7, s7, 12
	s_sub_i32 s6, s6, s7
	s_mul_i32 s6, s6, 0xc0
	s_mov_b32 s7, 0
	v_lshl_add_u64 v[246:247], s[6:7], 2, v[126:127]
	s_and_saveexec_b64 s[100:101], s[36:37]
	global_load_dword v237, v[246:247], off
	s_mov_b64 exec, s[100:101]
.Lside_ret:
	s_cmp_eq_u32 s9, 0
	s_cbranch_scc1 .Lside_ret_a
	s_cmp_eq_u32 s9, 1
	s_cbranch_scc1 .Lside_ret_b
	s_branch .Lside_ret_p
